# v24 + gate staging-tile XOR swizzle (registers moved to v248-v255) + mlaprep DPP wave reductions
# speedup vs baseline: 1.0063x; 1.0063x over previous
; DI void phase_gate(const Params& p, int ch) {
;     ...
;   float w0[3][8], b0[8];
;   { const int c0 = ch * 256 + (tid & 31) * 8;
; #pragma unroll
;     for (int i = 0; i < 8; ++i) { b0[i] = cb[c0 + i];
; #pragma unroll
;       for (int t = 0; t < 3; ++t) w0[t][i] = cw[t * 6144 + c0 + i]; } }
;   for (int it = blockIdx.x; it < T / 64; it += gridDim.x) {
;     const int tok0 = it * 64;
;     { int cl = tid >> 1, th = (tid & 1) * 32; const bft* s = yT + (size_t)cl * T + tok0 + th;
; #pragma unroll
;       for (int q = 0; q < 4; ++q) { u32x4 v = *(const u32x4*)(s + q * 8);
; #pragma unroll
;         for (int k = 0; k < 4; ++k) { tile[cl * 65 + th + q * 8 + 2 * k] = __uint_as_float(v[k] << 16); tile[cl * 65 + th + q * 8 + 2 * k + 1] = __uint_as_float(v[k] & 0xffff0000u); } } }
.LBB0_1706:
	s_or_b64 exec, exec, s[0:1]
	v_mov_b32_e32 v45, v180
	s_and_b64 vcc, exec, s[8:9]
	s_waitcnt lgkmcnt(0)
	s_barrier
	s_cbranch_vccnz .LBB0_1715
	v_lshlrev_b32_e32 v0, 3, v45
	v_and_b32_e32 v44, 0xf8, v0
	v_or_b32_e32 v0, s75, v44
	v_readlane_b32 s8, v240, 49
	v_lshlrev_b64 v[6:7], 2, v[0:1]
	v_readlane_b32 s9, v240, 50
	s_movk_i32 s0, 0x6000
	v_readlane_b32 s10, v240, 51
	v_lshl_add_u64 v[30:31], s[8:9], 0, v[6:7]
	v_add_co_u32_e32 v18, vcc, s0, v30
	s_mov_b32 s0, 0xc000
	s_nop 0
	v_addc_co_u32_e32 v19, vcc, 0, v31, vcc
	v_readlane_b32 s11, v240, 52
	v_add_co_u32_e32 v22, vcc, s0, v30
	s_mov_b64 s[0:1], 0x6000
	v_lshl_add_u64 v[10:11], s[10:11], 0, v[6:7]
	v_lshl_add_u64 v[26:27], v[30:31], 0, s[0:1]
	s_mov_b64 s[0:1], 0xc000
	global_load_dwordx4 v[2:5], v[10:11], off
	global_load_dwordx4 v[6:9], v[30:31], off
	s_nop 0
	global_load_dwordx4 v[10:13], v[10:11], off offset:16
	s_nop 0
	global_load_dwordx4 v[14:17], v[30:31], off offset:16
	v_addc_co_u32_e32 v23, vcc, 0, v31, vcc
	v_lshl_add_u64 v[30:31], v[30:31], 0, s[0:1]
	global_load_dwordx4 v[18:21], v[18:19], off
	s_and_b32 s0, s75, 0x300
	global_load_dwordx4 v[22:25], v[22:23], off
	v_ashrrev_i32_e32 v0, 1, v45
	global_load_dwordx4 v[26:29], v[26:27], off offset:16
	v_mov_b64_e32 v[34:35], s[82:83]
	global_load_dwordx4 v[30:33], v[30:31], off offset:16
	s_lshl_b32 s8, s0, 1
	s_mov_b32 s0, 0x18000
	v_lshlrev_b32_e32 v36, 5, v45
	v_mad_i64_i32 v[34:35], s[0:1], v0, s0, v[34:35]
	v_and_b32_e32 v36, 32, v36
	s_movk_i32 s1, 0x104
	v_mul_lo_u32 v37, v0, s1
	s_add_u32 s0, s68, s8
	v_lshlrev_b32_e32 v0, 1, v36
	v_mad_u32_u24 v56, v44, s1, 16
	v_bfe_u32 v254, v45, 5, 3
	v_bfe_u32 v255, v45, 2, 2
	v_lshlrev_b32_e32 v255, 1, v255
	v_xor_b32_e32 v255, v254, v255
	v_sub_u32_e32 v255, v255, v254
	v_lshl_add_u32 v56, v255, 2, v56
	s_addc_u32 s1, s69, 0
	v_lshl_add_u64 v[46:47], v[34:35], 0, v[0:1]
	v_lshlrev_b32_e32 v0, 1, v44
	v_lshlrev_b32_e32 v38, 2, v36
	v_lshl_add_u64 v[48:49], s[0:1], 0, v[0:1]
	v_readlane_b32 s0, v240, 10
	v_add3_u32 v57, 16, v37, v38
	v_bfe_u32 v248, v45, 6, 2
	v_xor_b32_e32 v249, 0, v248
	v_lshl_add_u32 v250, v249, 3, v57
	v_xor_b32_e32 v249, 1, v248
	v_lshl_add_u32 v251, v249, 3, v57
	v_xor_b32_e32 v249, 2, v248
	v_lshl_add_u32 v252, v249, 3, v57
	v_xor_b32_e32 v249, 3, v248
	v_lshl_add_u32 v253, v249, 3, v57
	s_mov_b32 s10, s0
	v_readlane_b32 s1, v240, 11
	s_waitcnt vmcnt(6)
	v_mov_b32_e32 v52, v7
	v_mov_b32_e32 v50, v3
	v_mov_b32_e32 v51, v5
	v_mov_b32_e32 v53, v9
	v_mov_b32_e32 v3, v4
	v_mov_b32_e32 v7, v8
	s_waitcnt vmcnt(5)
	v_mov_b32_e32 v4, v11
	v_mov_b32_e32 v5, v13
	s_waitcnt vmcnt(4)
	v_mov_b32_e32 v8, v15
	v_mov_b32_e32 v9, v17
	v_mov_b32_e32 v11, v12
	v_mov_b32_e32 v15, v16
	s_waitcnt vmcnt(3)
	v_mov_b32_e32 v12, v19
	v_mov_b32_e32 v13, v21
	s_waitcnt vmcnt(2)
	v_mov_b32_e32 v16, v23
	v_mov_b32_e32 v17, v25
	v_mov_b32_e32 v19, v20
	v_mov_b32_e32 v23, v24
	s_waitcnt vmcnt(1)
	v_mov_b32_e32 v20, v27
	v_mov_b32_e32 v21, v29
	s_waitcnt vmcnt(0)
	v_mov_b32_e32 v24, v31
	v_mov_b32_e32 v25, v33
	v_mov_b32_e32 v27, v28
	v_mov_b32_e32 v31, v32
	s_branch .LBB0_1709

; DI void phase_gate(const Params& p, int ch) {
;     ...
;   for (int it = blockIdx.x; it < T / 64; it += gridDim.x) {
;     const int tok0 = it * 64;
;     { int cl = tid >> 1, th = (tid & 1) * 32; const bft* s = yT + (size_t)cl * T + tok0 + th;
; #pragma unroll
;       for (int q = 0; q < 4; ++q) { u32x4 v = *(const u32x4*)(s + q * 8);
; #pragma unroll
;         for (int k = 0; k < 4; ++k) { tile[cl * 65 + th + q * 8 + 2 * k] = __uint_as_float(v[k] << 16); tile[cl * 65 + th + q * 8 + 2 * k + 1] = __uint_as_float(v[k] & 0xffff0000u); } } }
;     __syncthreads();
; #pragma unroll 1
;     for (int rr = 0; rr < 4; ++rr) { int e = tid + rr * 512; int tl = e >> 5, cg = e & 31; int tok = tok0 + tl, cc = cg * 8, c = ch * 256 + cc; int pos = tok_pos(tok), L = tok_len(tok);
;       const bft* zr = Z + (size_t)tok * 1024; u32x4 zero = {0, 0, 0, 0};
;       u32x4 xm = pos > 0 ? *(const u32x4*)(zr - 1024 + cc) : zero, x0 = *(const u32x4*)(zr + cc), xp = pos < L - 1 ? *(const u32x4*)(zr + 1024 + cc) : zero, gt = *(const u32x4*)(zr + 768 + cc);
.LBB0_1709:
	s_lshl_b32 s0, s10, 6
	s_ashr_i32 s1, s0, 31
	v_lshl_add_u64 v[28:29], s[0:1], 1, v[46:47]
	global_load_dwordx4 v[32:35], v[28:29], off offset:48
	global_load_dwordx4 v[36:39], v[28:29], off offset:32
	global_load_dwordx4 v[40:43], v[28:29], off offset:16
	global_load_dwordx4 v[58:61], v[28:29], off
	v_ashrrev_i32_e32 v218, 5, v45
	v_add_u32_e32 v220, s0, v218
	v_cmp_gt_i32_e32 vcc, s29, v220
	v_ashrrev_i32_e32 v221, 31, v220
	v_lshlrev_b64 v[222:223], 11, v[220:221]
	s_nop 0
	v_cndmask_b32_e32 v219, v152, v153, vcc
	v_and_b32_e32 v241, v219, v220
	v_lshl_add_u64 v[222:223], s[76:77], 0, v[222:223]
	v_cmp_ne_u32_e32 vcc, 0, v241
	v_lshlrev_b32_e32 v224, 1, v44
	v_mov_b32_e32 v225, 0
	v_mov_b32_e32 v228, 0
	v_mov_b32_e32 v229, 0
	v_mov_b32_e32 v230, 0
	v_mov_b32_e32 v231, 0
	v_lshl_add_u64 v[226:227], v[222:223], 0, v[224:225]
	s_and_saveexec_b64 s[8:9], vcc
	global_load_dwordx4 v[228:231], v[226:227], off offset:-2048
	s_or_b64 exec, exec, s[8:9]
	global_load_dwordx4 v[232:235], v[226:227], off
	v_cmp_ne_u32_e32 vcc, v241, v219
	v_mov_b32_e32 v236, 0
	v_mov_b32_e32 v237, 0
	v_mov_b32_e32 v238, 0
	v_mov_b32_e32 v239, 0
	s_and_saveexec_b64 s[8:9], vcc
	global_load_dwordx4 v[236:239], v[226:227], off offset:2048
	s_or_b64 exec, exec, s[8:9]
	global_load_dwordx4 v[244:247], v[226:227], off offset:1536
	s_mov_b32 s1, 0
	s_waitcnt vmcnt(0)
	v_lshlrev_b32_e32 v0, 16, v58
	v_and_b32_e32 v28, 0xffff0000, v58
	ds_write2_b32 v250, v0, v28 offset1:1
	v_lshlrev_b32_e32 v0, 16, v59
	v_and_b32_e32 v28, 0xffff0000, v59
	ds_write2_b32 v251, v0, v28 offset1:1
	v_lshlrev_b32_e32 v0, 16, v60
	v_and_b32_e32 v28, 0xffff0000, v60
	ds_write2_b32 v252, v0, v28 offset1:1
	v_lshlrev_b32_e32 v0, 16, v61
	v_and_b32_e32 v28, 0xffff0000, v61
	ds_write2_b32 v253, v0, v28 offset1:1
	v_lshlrev_b32_e32 v0, 16, v40
	v_and_b32_e32 v28, 0xffff0000, v40
	ds_write2_b32 v250, v0, v28 offset0:8 offset1:9
	v_lshlrev_b32_e32 v0, 16, v41
	v_and_b32_e32 v28, 0xffff0000, v41
	ds_write2_b32 v251, v0, v28 offset0:8 offset1:9
	v_lshlrev_b32_e32 v0, 16, v42
	v_and_b32_e32 v28, 0xffff0000, v42
	ds_write2_b32 v252, v0, v28 offset0:8 offset1:9
	v_lshlrev_b32_e32 v0, 16, v43
	v_and_b32_e32 v28, 0xffff0000, v43
	ds_write2_b32 v253, v0, v28 offset0:8 offset1:9
	v_lshlrev_b32_e32 v0, 16, v36
	v_and_b32_e32 v28, 0xffff0000, v36
	ds_write2_b32 v250, v0, v28 offset0:16 offset1:17
	v_lshlrev_b32_e32 v0, 16, v37
	v_and_b32_e32 v28, 0xffff0000, v37
	ds_write2_b32 v251, v0, v28 offset0:16 offset1:17
	v_lshlrev_b32_e32 v0, 16, v38
	v_and_b32_e32 v28, 0xffff0000, v38
	ds_write2_b32 v252, v0, v28 offset0:16 offset1:17
	v_lshlrev_b32_e32 v0, 16, v39
	v_and_b32_e32 v28, 0xffff0000, v39
	ds_write2_b32 v253, v0, v28 offset0:16 offset1:17
	v_lshlrev_b32_e32 v0, 16, v32
	v_and_b32_e32 v28, 0xffff0000, v32
	ds_write2_b32 v250, v0, v28 offset0:24 offset1:25
	v_lshlrev_b32_e32 v0, 16, v33
	v_and_b32_e32 v28, 0xffff0000, v33
	ds_write2_b32 v251, v0, v28 offset0:24 offset1:25
	v_lshlrev_b32_e32 v0, 16, v34
	v_and_b32_e32 v28, 0xffff0000, v34
	ds_write2_b32 v252, v0, v28 offset0:24 offset1:25
	v_lshlrev_b32_e32 v0, 16, v35
	v_and_b32_e32 v28, 0xffff0000, v35
	ds_write2_b32 v253, v0, v28 offset0:24 offset1:25
	s_waitcnt lgkmcnt(0)
	s_barrier
	s_branch .LBB0_1711
